# adaLN partial sums of layers 2 and 3 moved from the prologue to the idle tail of the layer-0 scores GEMM phase (same code, non-temporal weight loads), their final reduction done by idle scan waves
# speedup vs baseline: 1.0979x; 1.0017x over previous
; #define LAS __attribute__((address_space(3)))
; __device__ __forceinline__ float siluf_(float x) { return x / (1.0f + __expf(-x)); }
; __device__ __forceinline__ void phase_prologue(KP P, const Ctx& c) {
;     ...
;         for (int un = blockIdx.x; un < 4 * 24 * 8; un += gridDim.x) {
;             const int layer = un / 192, r = un % 192, nb = r / 8, kc = r % 8;
;             __syncthreads();
;             for (int i = c.tid; i < 5 * 256; i += 512) { const int v = i >> 8, k = kc * 256 + (i & 255); const float x = v < 4 ? P->in[I_C][v * D + k] : P->in[I_CCTX][k]; sl[i] = siluf_(x); }
;             __syncthreads();
;             const int cg = c.tid & 127, ks = c.tid >> 7;
;             const float* w = P->in[I_ADAW] + ((size_t)layer * D + kc * 256 + ks * 64) * 12288 + nb * 512 + cg * 4;
;             f32x4 a0 = (f32x4){0.f, 0.f, 0.f, 0.f}, a1 = a0, a2 = a0, a3 = a0, a4 = a0;
;             f32x4 wn[8];
; #pragma unroll
;             for (int i = 0; i < 8; ++i) wn[i] = *(const f32x4*)(w + (size_t)i * 12288);
; #pragma unroll 1
;             for (int k0 = 0; k0 < 64; k0 += 8) { f32x4 wc[8];
; #pragma unroll
;                 for (int i = 0; i < 8; ++i) wc[i] = wn[i];
;                 if (k0 + 8 < 64) {
; #pragma unroll
;                     for (int i = 0; i < 8; ++i) wn[i] = *(const f32x4*)(w + (size_t)(k0 + 8 + i) * 12288); }
; #pragma unroll
;                 for (int i = 0; i < 8; ++i) { const f32x4 wv = wc[i]; const int kk = ks * 64 + k0 + i;
;                     a0 += wv * sl[kk]; a1 += wv * sl[256 + kk]; a2 += wv * sl[512 + kk]; a3 += wv * sl[768 + kk]; a4 += wv * sl[1024 + kk]; } }
;             LAS float* rp = red + (ks * 5) * 512 + cg * 4;
;             *(LAS f32x4*)(rp) = a0; *(LAS f32x4*)(rp + 512) = a1; *(LAS f32x4*)(rp + 1024) = a2; *(LAS f32x4*)(rp + 1536) = a3; *(LAS f32x4*)(rp + 2048) = a4;
;             __syncthreads();
;             for (int i = c.tid; i < 5 * 512; i += 512) { const int v = i >> 9, n = i & 511;
;                 const float sum = (red[(0 * 5 + v) * 512 + n] + red[(1 * 5 + v) * 512 + n]) + (red[(2 * 5 + v) * 512 + n] + red[(3 * 5 + v) * 512 + n]);
;                 ((float*)(ws + WS_MODP))[((size_t)(layer * 8 + kc) * 5 + v) * 12288 + nb * 512 + n] = sum; }
;         }
.LBB0_7:
	s_or_b64 exec, exec, s[26:27]
	s_add_i32 s47, s47, s3
	s_movk_i32 s96, 0x2ff
	s_cmpk_eq_i32 s3, 0x100
	s_cselect_b32 s96, 0x17f, s96
	s_cmp_gt_i32 s47, s96
	s_cbranch_scc1 .LBB0_33

; #define PROBE_REP(bit) for (int _rep = 0; _rep < (((PROBE) >> (bit)) & 1) + 1; ++_rep)
; __device__ __forceinline__ float siluf_(float x) { return x / (1.0f + __expf(-x)); }
; __device__ __forceinline__ KP kp_fresh() { KP p = (KP)__builtin_amdgcn_kernarg_segment_ptr(); asm volatile("" : "+s"(p)); return p; }
; __device__ __forceinline__ void phase_prologue(KP P, const Ctx& c) {
;     ...
;         for (int un = blockIdx.x; un < 4 * 24 * 8; un += gridDim.x) {
;             const int layer = un / 192, r = un % 192, nb = r / 8, kc = r % 8;
;             __syncthreads();
;             for (int i = c.tid; i < 5 * 256; i += 512) { const int v = i >> 8, k = kc * 256 + (i & 255); const float x = v < 4 ? P->in[I_C][v * D + k] : P->in[I_CCTX][k]; sl[i] = siluf_(x); }
;             __syncthreads();
;             const int cg = c.tid & 127, ks = c.tid >> 7;
;             const float* w = P->in[I_ADAW] + ((size_t)layer * D + kc * 256 + ks * 64) * 12288 + nb * 512 + cg * 4;
;             f32x4 a0 = (f32x4){0.f, 0.f, 0.f, 0.f}, a1 = a0, a2 = a0, a3 = a0, a4 = a0;
;             f32x4 wn[8];
; #pragma unroll
;             for (int i = 0; i < 8; ++i) wn[i] = *(const f32x4*)(w + (size_t)i * 12288);
; template <int LAYER, bool LAST> __device__ __forceinline__ void peer_phases(LAS unsigned char* lds, const XcdBarrier& bar) {
;     ...
;     PROBE_REP(2) { KP P = kp_fresh(); unsigned char* ws = P->ws; GPlain g{(const bf16_t*)(ws + WS_H2), (const bf16_t*)(ws + WS_WQ) + (size_t)LAYER * D * D, D, D, D}; EpiF32Plain E{(float*)(ws + WS_S), D}; run_gemm(lds, g, D, E, LAST ? 4 : 0);
;         if (!LAST && _rep == 0) { constexpr int NR = 8 * 16384, SH = (NR + 2) / 3; const int lo = LAYER * SH, hi = (LAYER == 2) ? NR : (LAYER + 1) * SH;
;             if ((int)gridDim.x == 256) { if ((int)blockIdx.x >= 32) peer_convert_rows(kp_fresh(), make_ctx(lds), lo, hi, (int)blockIdx.x - 32, 224); }
;             else peer_convert_rows(kp_fresh(), make_ctx(lds), lo, hi, (int)blockIdx.x, (int)gridDim.x); }
.LBB0_1061:
	v_readlane_b32 s3, v244, 4
	s_cmpk_lg_i32 s3, 0x100
	s_cbranch_scc1 .Lj4t_skip
	s_cmp_lt_u32 s2, 32
	s_cbranch_scc1 .Lj4t_skip
	v_writelane_b32 v247, s6, 0
	v_writelane_b32 v247, s7, 1
	v_writelane_b32 v247, s24, 2
	v_writelane_b32 v247, s25, 3
	v_writelane_b32 v247, s26, 4
	v_writelane_b32 v247, s27, 5
	v_writelane_b32 v247, s28, 6
	v_writelane_b32 v247, s29, 7
	v_writelane_b32 v247, s30, 8
	v_writelane_b32 v247, s31, 9
	v_writelane_b32 v247, s35, 10
	v_writelane_b32 v247, s36, 11
	v_writelane_b32 v247, s37, 12
	v_mov_b32_e32 v240, v1
	v_mov_b32_e32 v241, v96
	v_mov_b32_e32 v242, v97
	v_mov_b32_e32 v243, v98
	v_mov_b32_e32 v245, v99
	v_mov_b32_e32 v246, v101
	s_mov_b64 s[18:19], s[94:95]
	s_load_dwordx2 s[16:17], s[18:19], 0x130
	v_mov_b32_e32 v86, v0
	s_movk_i32 s3, 0xe0
	s_waitcnt vmcnt(0) lgkmcnt(0)
	s_barrier
	v_lshlrev_b32_e32 v1, 2, v86
	v_ashrrev_i32_e32 v3, 7, v86
	v_and_b32_e32 v2, 0x1fc, v1
	s_movk_i32 s6, 0x2700
	v_lshlrev_b32_e32 v88, 6, v3
	v_lshl_add_u32 v100, v3, 8, 0
	v_mul_lo_u32 v3, v3, s6
	v_lshlrev_b32_e32 v4, 2, v2
	v_add3_u32 v101, v100, v3, v4
	v_max_i32_e32 v3, 0x800, v86
	v_mov_b32_e32 v91, 0
	v_and_b32_e32 v90, 0x7fc, v1
	v_sub_u32_e32 v3, v3, v86
	s_waitcnt lgkmcnt(0)
	v_lshl_add_u64 v[4:5], s[16:17], 0, v[90:91]
	s_mov_b64 s[8:9], 0x200000
	v_add_u32_e32 v3, 0x1ff, v3
	s_load_dwordx2 s[20:21], s[18:19], 0x20
	v_lshl_add_u64 v[92:93], v[4:5], 0, s[8:9]
	v_lshrrev_b32_e32 v4, 9, v3
	s_movk_i32 s8, 0x1ff
	v_add_u32_e32 v5, 1, v4
	v_cmp_lt_u32_e64 s[8:9], s8, v3
	v_and_b32_e32 v3, 0xfffffe, v5
	v_add_u32_e32 v4, -1, v4
	v_lshl_add_u32 v102, v3, 9, v86
	v_cmp_ne_u32_e64 s[14:15], v5, v3
	v_and_b32_e32 v3, 0x7f, v86
	v_lshrrev_b32_e32 v6, 1, v4
	v_cmp_lt_u32_e64 s[10:11], 1, v4
	v_and_b32_e32 v4, 2, v4
	v_add_u32_e32 v104, 0, v90
	v_lshlrev_b32_e32 v90, 4, v3
	s_movk_i32 s4, 0x500
	s_movk_i32 s6, 0xa00
	v_add_u32_e32 v6, 1, v6
	v_cmp_eq_u32_e64 s[12:13], 0, v4
	v_add_u32_e32 v105, 0, v1
	s_waitcnt lgkmcnt(0)
	v_lshl_add_u64 v[4:5], s[20:21], 0, v[90:91]
	s_mov_b64 s[22:23], 0xb4000
	v_cmp_gt_i32_e64 s[4:5], s4, v86
	v_ashrrev_i32_e32 v89, 31, v88
	v_cmp_gt_i32_e64 s[6:7], s6, v86
	v_add_u32_e32 v87, 0x200, v86
	v_and_b32_e32 v103, -2, v6
	v_lshl_add_u64 v[94:95], v[4:5], 0, s[22:23]
	v_add_u32_e32 v106, 0x1400, v105
	s_movk_i32 s35, 0x2ff
	s_mov_b32 s36, 0xc000
	v_mov_b64_e32 v[96:97], s[20:21]
	v_lshlrev_b32_e32 v90, 2, v2
	s_mov_b32 s37, 0x18000
	s_mov_b32 s40, 0x24000
	s_mov_b32 s41, 0x30000
	s_mov_b32 s43, 0x3c000
	s_mov_b32 s44, 0x48000
	s_mov_b32 s45, 0x54000
	s_mov_b64 s[20:21], 0x60000
	s_movk_i32 s46, 0x7ff
	s_add_i32 s47, s2, 0x160
	s_branch .Lj4t_8

; __device__ __forceinline__ float siluf_(float x) { return x / (1.0f + __expf(-x)); }
; __device__ __forceinline__ void phase_prologue(KP P, const Ctx& c) {
;     ...
;             __syncthreads();
;             for (int i = c.tid; i < 5 * 256; i += 512) { const int v = i >> 8, k = kc * 256 + (i & 255); const float x = v < 4 ? P->in[I_C][v * D + k] : P->in[I_CCTX][k]; sl[i] = siluf_(x); }
;             __syncthreads();
;             const int cg = c.tid & 127, ks = c.tid >> 7;
;             const float* w = P->in[I_ADAW] + ((size_t)layer * D + kc * 256 + ks * 64) * 12288 + nb * 512 + cg * 4;
;             f32x4 a0 = (f32x4){0.f, 0.f, 0.f, 0.f}, a1 = a0, a2 = a0, a3 = a0, a4 = a0;
;             f32x4 wn[8];
; #pragma unroll
;             for (int i = 0; i < 8; ++i) wn[i] = *(const f32x4*)(w + (size_t)i * 12288);
.Lj4t_15:
	s_or_b64 exec, exec, s[24:25]
	s_sext_i32_i16 s23, s23
	s_lshr_b32 s23, s23, 3
	s_sext_i32_i16 s26, s23
	s_ashr_i32 s23, s22, 31
	s_lshl_b64 s[24:25], s[22:23], 11
	s_ashr_i32 s23, s31, 31
	s_add_u32 s24, s31, s24
	s_addc_u32 s25, s23, s25
	v_lshl_add_u64 v[34:35], s[24:25], 0, v[88:89]
	v_mad_u64_u32 v[2:3], s[24:25], v34, s36, v[96:97]
	s_lshl_b32 s24, s26, 9
	s_ashr_i32 s25, s24, 31
	v_mad_i32_i24 v3, v35, s36, v3
	s_lshl_b64 s[26:27], s[24:25], 2
	v_lshl_add_u64 v[2:3], v[2:3], 0, s[26:27]
	v_lshl_add_u64 v[2:3], v[2:3], 0, v[90:91]
	v_add_co_u32_e32 v4, vcc, s36, v2
	s_waitcnt lgkmcnt(0)
	s_nop 0
	v_addc_co_u32_e32 v5, vcc, 0, v3, vcc
	s_barrier
	global_load_dwordx4 v[26:29], v[2:3], off nt
	global_load_dwordx4 v[22:25], v[4:5], off nt
	v_add_co_u32_e32 v4, vcc, s37, v2
	v_mov_b64_e32 v[36:37], s[26:27]
	s_nop 0
	v_addc_co_u32_e32 v5, vcc, 0, v3, vcc
	v_add_co_u32_e32 v6, vcc, s40, v2
	v_mad_u64_u32 v[36:37], s[26:27], v34, s36, v[36:37]
	s_nop 0
	v_addc_co_u32_e32 v7, vcc, 0, v3, vcc
	global_load_dwordx4 v[30:33], v[4:5], off nt
	global_load_dwordx4 v[14:17], v[6:7], off nt
	v_add_co_u32_e32 v4, vcc, s41, v2
	v_mad_i32_i24 v37, v35, s36, v37
	s_nop 0
	v_addc_co_u32_e32 v5, vcc, 0, v3, vcc
	v_add_co_u32_e32 v6, vcc, s43, v2
	v_mov_b32_e32 v58, 0
	s_nop 0
	v_addc_co_u32_e32 v7, vcc, 0, v3, vcc
	global_load_dwordx4 v[18:21], v[4:5], off nt
	global_load_dwordx4 v[10:13], v[6:7], off nt
	v_add_co_u32_e32 v4, vcc, s44, v2
	s_mov_b32 s23, 0
	s_nop 0
	v_addc_co_u32_e32 v5, vcc, 0, v3, vcc
	v_add_co_u32_e32 v2, vcc, s45, v2
	v_lshl_add_u64 v[98:99], v[94:95], 0, v[36:37]
	s_nop 0
	v_addc_co_u32_e32 v3, vcc, 0, v3, vcc
	global_load_dwordx4 v[6:9], v[4:5], off nt
	s_nop 0
	global_load_dwordx4 v[2:5], v[2:3], off nt
	v_mov_b32_e32 v107, v100
	v_mov_b32_e32 v59, v58
	v_mov_b32_e32 v60, v58
	v_mov_b32_e32 v61, v58
	v_mov_b32_e32 v34, v58
	v_mov_b32_e32 v35, v58
	v_mov_b32_e32 v36, v58
	v_mov_b32_e32 v37, v58
	v_mov_b32_e32 v38, v58
	v_mov_b32_e32 v39, v58
	v_mov_b32_e32 v40, v58
	v_mov_b32_e32 v41, v58
	v_mov_b32_e32 v42, v58
	v_mov_b32_e32 v43, v58
	v_mov_b32_e32 v44, v58
	v_mov_b32_e32 v45, v58
	v_mov_b32_e32 v46, v58
	v_mov_b32_e32 v47, v58
	v_mov_b32_e32 v48, v58
	v_mov_b32_e32 v49, v58
	s_branch .Lj4t_17

; __device__ __forceinline__ void phase_prologue(KP P, const Ctx& c) {
;     ...
; #pragma unroll 1
;             for (int k0 = 0; k0 < 64; k0 += 8) { f32x4 wc[8];
; #pragma unroll
;                 for (int i = 0; i < 8; ++i) wc[i] = wn[i];
;                 if (k0 + 8 < 64) {
; #pragma unroll
;                     for (int i = 0; i < 8; ++i) wn[i] = *(const f32x4*)(w + (size_t)(k0 + 8 + i) * 12288); }
.Lj4t_17:
	s_cmp_gt_u32 s23, 55
	s_cselect_b64 s[26:27], -1, 0
	s_and_b64 vcc, exec, s[26:27]
	s_waitcnt vmcnt(7)
	v_mov_b32_e32 v50, v26
	v_mov_b32_e32 v51, v27
	v_mov_b32_e32 v52, v28
	v_mov_b32_e32 v53, v29
	s_waitcnt vmcnt(6)
	v_mov_b32_e32 v54, v22
	v_mov_b32_e32 v55, v23
	v_mov_b32_e32 v56, v24
	v_mov_b32_e32 v57, v25
	s_waitcnt vmcnt(5)
	v_mov_b32_e32 v62, v30
	v_mov_b32_e32 v63, v31
	v_mov_b32_e32 v64, v32
	v_mov_b32_e32 v65, v33
	s_waitcnt vmcnt(4)
	v_mov_b32_e32 v66, v14
	v_mov_b32_e32 v67, v15
	v_mov_b32_e32 v68, v16
	v_mov_b32_e32 v69, v17
	s_waitcnt vmcnt(3)
	v_mov_b32_e32 v70, v18
	v_mov_b32_e32 v71, v19
	v_mov_b32_e32 v72, v20
	v_mov_b32_e32 v73, v21
	s_waitcnt vmcnt(2)
	v_mov_b32_e32 v74, v10
	v_mov_b32_e32 v75, v11
	v_mov_b32_e32 v76, v12
	v_mov_b32_e32 v77, v13
	s_waitcnt vmcnt(1)
	v_mov_b32_e32 v78, v6
	v_mov_b32_e32 v79, v7
	v_mov_b32_e32 v80, v8
	v_mov_b32_e32 v81, v9
	s_waitcnt vmcnt(0)
	v_mov_b32_e32 v82, v2
	v_mov_b32_e32 v83, v3
	v_mov_b32_e32 v84, v4
	v_mov_b32_e32 v85, v5
	s_cbranch_vccnz .Lj4t_16
	v_add_co_u32_e32 v50, vcc, 0xfffac000, v98
	s_nop 1
	v_addc_co_u32_e32 v51, vcc, -1, v99, vcc
	v_add_co_u32_e32 v54, vcc, 0xfffb8000, v98
	s_nop 1
	v_addc_co_u32_e32 v55, vcc, -1, v99, vcc
	v_add_co_u32_e32 v62, vcc, 0xfffc4000, v98
	global_load_dwordx4 v[50:53], v[50:51], off nt
	s_nop 0
	global_load_dwordx4 v[54:57], v[54:55], off nt
	v_addc_co_u32_e32 v63, vcc, -1, v99, vcc
	v_add_co_u32_e32 v66, vcc, 0xfffd0000, v98
	s_nop 1
	v_addc_co_u32_e32 v67, vcc, -1, v99, vcc
	v_add_co_u32_e32 v70, vcc, 0xfffdc000, v98
	global_load_dwordx4 v[62:65], v[62:63], off nt
	s_nop 0
	global_load_dwordx4 v[66:69], v[66:67], off nt
	v_addc_co_u32_e32 v71, vcc, -1, v99, vcc
	v_add_co_u32_e32 v74, vcc, 0xfffe8000, v98
	s_nop 1
	v_addc_co_u32_e32 v75, vcc, -1, v99, vcc
	v_add_co_u32_e32 v78, vcc, 0xffff4000, v98
	global_load_dwordx4 v[70:73], v[70:71], off nt
	s_nop 0
	global_load_dwordx4 v[74:77], v[74:75], off nt
	v_addc_co_u32_e32 v79, vcc, -1, v99, vcc
	global_load_dwordx4 v[78:81], v[78:79], off nt
	s_nop 0
	global_load_dwordx4 v[82:85], v[98:99], off nt
	s_branch .Lj4t_16

; __device__ __forceinline__ void phase_prologue(KP P, const Ctx& c) {
;     ...
;         }
;         __syncthreads();
.Lj4t_done:
	s_waitcnt vmcnt(0) lgkmcnt(0)
	s_barrier
	v_readlane_b32 s6, v247, 0
	v_readlane_b32 s7, v247, 1
	v_readlane_b32 s24, v247, 2
	v_readlane_b32 s25, v247, 3
	v_readlane_b32 s26, v247, 4
	v_readlane_b32 s27, v247, 5
	v_readlane_b32 s28, v247, 6
	v_readlane_b32 s29, v247, 7
	v_readlane_b32 s30, v247, 8
	v_readlane_b32 s31, v247, 9
	v_readlane_b32 s35, v247, 10
	v_readlane_b32 s36, v247, 11
	v_readlane_b32 s37, v247, 12
	v_mov_b32_e32 v1, v240
	v_mov_b32_e32 v96, v241
	v_mov_b32_e32 v97, v242
	v_mov_b32_e32 v98, v243
	v_mov_b32_e32 v99, v245
	v_mov_b32_e32 v101, v246

; __device__ __forceinline__ void phase_modfin(KP P, const Ctx& c) {
;     for (int i = c.gtid; i < 4 * 5 * 12288; i += c.ngt) { const int n = i % 12288, lv = i / 12288, l = lv / 5, v = lv % 5;
;         float s = P->in[I_ADAB][l * 12288 + n];
;         for (int kc = 0; kc < 8; ++kc) s += ((const float*)(P->ws + WS_MODP))[((size_t)(l * 8 + kc) * 5 + v) * 12288 + n];
;         ((float*)(P->ws + WS_MOD))[i] = s; }
.Lrw_tr:
	s_cmp_lg_u32 s8, 0
	s_cbranch_scc1 .Lrw_mf_done
	s_lshr_b32 s61, s63, 6
	s_sub_i32 s61, s61, 4
	s_lshl_b32 s62, s2, 2
	s_add_i32 s61, s61, s62
	s_load_dwordx2 s[64:65], s[94:95], 0x28
	s_load_dwordx2 s[68:69], s[94:95], 0x130
	v_and_b32_e32 v102, 63, v0
	v_lshl_or_b32 v102, s61, 6, v102
	v_add_u32_e32 v102, 0x1e000, v102
	s_mov_b32 s70, 0
.Lrw_mf_loop:
	v_lshrrev_b32_e32 v103, 12, v102
	v_mul_u32_u24_e32 v103, 0xaaab, v103
	v_lshrrev_b32_e32 v103, 17, v103
	v_mul_u32_u24_e32 v104, 0x3000, v103
	v_sub_u32_e32 v104, v102, v104
	v_cmp_lt_u32_e32 vcc, 14, v103
	s_nop 1
	v_cndmask_b32_e64 v105, 2, 3, vcc
	v_mul_u32_u24_e32 v106, 5, v105
	v_sub_u32_e32 v106, v103, v106
	v_mul_u32_u24_e32 v38, 0x3000, v105
	v_add_lshl_u32 v38, v38, v104, 2
	v_mul_u32_u24_e32 v39, 40, v105
	v_add_u32_e32 v39, v39, v106
	v_mul_u32_u24_e32 v39, 0x3000, v39
	v_add_lshl_u32 v39, v39, v104, 2
	v_add_u32_e32 v39, 0x200000, v39
	v_lshlrev_b32_e32 v40, 2, v102
	v_add_u32_e32 v40, 0xa00000, v40
	v_cmp_gt_u32_e32 vcc, 0x3c000, v102
	s_and_saveexec_b64 s[72:73], vcc
	s_waitcnt lgkmcnt(0)
	global_load_dword v41, v38, s[64:65]
	global_load_dword v42, v39, s[68:69]
	v_add_u32_e32 v39, 0x3c000, v39
	global_load_dword v43, v39, s[68:69]
	v_add_u32_e32 v39, 0x3c000, v39
	global_load_dword v44, v39, s[68:69]
	v_add_u32_e32 v39, 0x3c000, v39
	global_load_dword v45, v39, s[68:69]
	v_add_u32_e32 v39, 0x3c000, v39
	global_load_dword v46, v39, s[68:69]
	v_add_u32_e32 v39, 0x3c000, v39
	global_load_dword v47, v39, s[68:69]
	v_add_u32_e32 v39, 0x3c000, v39
	global_load_dword v48, v39, s[68:69]
	v_add_u32_e32 v39, 0x3c000, v39
	global_load_dword v49, v39, s[68:69]
	s_waitcnt vmcnt(7)
	v_add_f32_e32 v41, v41, v42
	s_waitcnt vmcnt(6)
	v_add_f32_e32 v41, v41, v43
	s_waitcnt vmcnt(5)
	v_add_f32_e32 v41, v41, v44
	s_waitcnt vmcnt(4)
	v_add_f32_e32 v41, v41, v45
	s_waitcnt vmcnt(3)
	v_add_f32_e32 v41, v41, v46
	s_waitcnt vmcnt(2)
	v_add_f32_e32 v41, v41, v47
	s_waitcnt vmcnt(1)
	v_add_f32_e32 v41, v41, v48
	s_waitcnt vmcnt(0)
	v_add_f32_e32 v41, v41, v49
	global_store_dword v40, v41, s[68:69]
	s_or_b64 exec, exec, s[72:73]
	v_add_u32_e32 v102, 0x10000, v102
	s_add_i32 s70, s70, 1
	s_cmp_lt_u32 s70, 2
	s_cbranch_scc1 .Lrw_mf_loop
